# v28 + LayerNorm phase output stores write-through (sc1) so the following grid barrier's L2 writeback finds less dirty data
# baseline (speedup 1.0000x reference)
.LBB0_985:
	s_waitcnt vmcnt(4)
	v_lshlrev_b32_e32 v144, 16, v226
	v_and_b32_e32 v145, 0xffff0000, v226
	v_lshlrev_b32_e32 v146, 16, v227
	v_and_b32_e32 v147, 0xffff0000, v227
	v_lshlrev_b32_e32 v136, 16, v228
	v_and_b32_e32 v137, 0xffff0000, v228
	v_lshlrev_b32_e32 v140, 16, v229
	v_and_b32_e32 v141, 0xffff0000, v229
	v_lshlrev_b32_e32 v138, 16, v230
	v_and_b32_e32 v139, 0xffff0000, v230
	v_lshlrev_b32_e32 v142, 16, v231
	v_and_b32_e32 v143, 0xffff0000, v231
	v_lshlrev_b32_e32 v86, 16, v232
	v_and_b32_e32 v87, 0xffff0000, v232
	v_lshlrev_b32_e32 v98, 16, v233
	v_and_b32_e32 v99, 0xffff0000, v233
	v_lshlrev_b32_e32 v88, 16, v234
	v_and_b32_e32 v89, 0xffff0000, v234
	v_lshlrev_b32_e32 v100, 16, v235
	v_and_b32_e32 v101, 0xffff0000, v235
	v_lshlrev_b32_e32 v78, 16, v236
	v_and_b32_e32 v79, 0xffff0000, v236
	v_lshlrev_b32_e32 v82, 16, v237
	v_and_b32_e32 v83, 0xffff0000, v237
	v_lshlrev_b32_e32 v80, 16, v238
	v_and_b32_e32 v81, 0xffff0000, v238
	v_lshlrev_b32_e32 v84, 16, v239
	v_and_b32_e32 v85, 0xffff0000, v239
	v_lshlrev_b32_e32 v74, 16, v240
	v_and_b32_e32 v75, 0xffff0000, v240
	v_lshlrev_b32_e32 v76, 16, v241
	s_andn2_b64 vcc, exec, s[20:21]
	v_and_b32_e32 v77, 0xffff0000, v241
	s_cbranch_vccnz .LBB0_987
	v_lshlrev_b32_e32 v148, 16, v174
	v_and_b32_e32 v149, 0xffff0000, v174
	v_lshlrev_b32_e32 v156, 16, v175
	v_and_b32_e32 v157, 0xffff0000, v175
	v_pk_add_f32 v[156:157], v[146:147], v[156:157]
	v_pk_add_f32 v[144:145], v[144:145], v[148:149]
	v_lshlrev_b32_e32 v146, 16, v176
	v_and_b32_e32 v147, 0xffff0000, v176
	v_lshlrev_b32_e32 v148, 16, v177
	v_and_b32_e32 v149, 0xffff0000, v177
	s_mov_b64 s[20:21], 0x1e400000
	v_pk_add_f32 v[140:141], v[140:141], v[148:149]
	v_pk_add_f32 v[136:137], v[136:137], v[146:147]
	v_lshl_add_u64 v[150:151], v[134:135], 0, s[20:21]
	v_cvt_pk_bf16_f32 v146, v144, v145
	v_cvt_pk_bf16_f32 v147, v156, v157
	v_cvt_pk_bf16_f32 v148, v136, v137
	v_cvt_pk_bf16_f32 v149, v140, v141
	global_store_dwordx4 v[150:151], v[146:149], off sc1
	v_lshlrev_b32_e32 v136, 16, v148
	v_and_b32_e32 v137, 0xffff0000, v148
	v_lshlrev_b32_e32 v140, 16, v149
	v_and_b32_e32 v141, 0xffff0000, v149
	v_lshlrev_b32_e32 v148, 16, v178
	v_and_b32_e32 v149, 0xffff0000, v178
	v_lshlrev_b32_e32 v150, 16, v179
	v_and_b32_e32 v151, 0xffff0000, v179
	v_pk_add_f32 v[142:143], v[142:143], v[150:151]
	v_pk_add_f32 v[138:139], v[138:139], v[148:149]
	v_lshlrev_b32_e32 v148, 16, v180
	v_and_b32_e32 v149, 0xffff0000, v180
	v_lshlrev_b32_e32 v150, 16, v181
	v_and_b32_e32 v151, 0xffff0000, v181
	s_mov_b64 s[20:21], 0x1e400400
	v_pk_add_f32 v[98:99], v[98:99], v[150:151]
	v_pk_add_f32 v[86:87], v[86:87], v[148:149]
	v_lshl_add_u64 v[152:153], v[134:135], 0, s[20:21]
	v_cvt_pk_bf16_f32 v148, v138, v139
	v_cvt_pk_bf16_f32 v149, v142, v143
	v_cvt_pk_bf16_f32 v150, v86, v87
	v_cvt_pk_bf16_f32 v151, v98, v99
	global_store_dwordx4 v[152:153], v[148:151], off sc1
	v_lshlrev_b32_e32 v138, 16, v148
	v_and_b32_e32 v139, 0xffff0000, v148
	v_lshlrev_b32_e32 v142, 16, v149
	v_and_b32_e32 v143, 0xffff0000, v149
	v_lshlrev_b32_e32 v86, 16, v150
	v_and_b32_e32 v87, 0xffff0000, v150
	v_lshlrev_b32_e32 v98, 16, v151
	v_and_b32_e32 v99, 0xffff0000, v151
	v_lshlrev_b32_e32 v148, 16, v182
	v_and_b32_e32 v149, 0xffff0000, v182
	v_lshlrev_b32_e32 v150, 16, v183
	v_and_b32_e32 v151, 0xffff0000, v183
	v_pk_add_f32 v[100:101], v[100:101], v[150:151]
	v_pk_add_f32 v[88:89], v[88:89], v[148:149]
	v_lshlrev_b32_e32 v148, 16, v184
	v_and_b32_e32 v149, 0xffff0000, v184
	v_lshlrev_b32_e32 v150, 16, v185
	v_and_b32_e32 v151, 0xffff0000, v185
	s_mov_b64 s[20:21], 0x1e400800
	v_pk_add_f32 v[82:83], v[82:83], v[150:151]
	v_pk_add_f32 v[78:79], v[78:79], v[148:149]
	v_lshl_add_u64 v[154:155], v[134:135], 0, s[20:21]
	v_cvt_pk_bf16_f32 v148, v88, v89
	v_cvt_pk_bf16_f32 v149, v100, v101
	v_cvt_pk_bf16_f32 v150, v78, v79
	v_cvt_pk_bf16_f32 v151, v82, v83
	global_store_dwordx4 v[154:155], v[148:151], off sc1
	v_lshlrev_b32_e32 v88, 16, v148
	v_and_b32_e32 v89, 0xffff0000, v148
	v_lshlrev_b32_e32 v100, 16, v149
	v_and_b32_e32 v101, 0xffff0000, v149
	v_lshlrev_b32_e32 v78, 16, v150
	v_and_b32_e32 v79, 0xffff0000, v150
	v_lshlrev_b32_e32 v82, 16, v151
	v_and_b32_e32 v83, 0xffff0000, v151
	v_lshlrev_b32_e32 v148, 16, v186
	v_and_b32_e32 v149, 0xffff0000, v186
	v_lshlrev_b32_e32 v150, 16, v187
	v_and_b32_e32 v151, 0xffff0000, v187
	v_pk_add_f32 v[84:85], v[84:85], v[150:151]
	v_pk_add_f32 v[80:81], v[80:81], v[148:149]
	v_lshlrev_b32_e32 v148, 16, v188
	v_and_b32_e32 v149, 0xffff0000, v188
	v_lshlrev_b32_e32 v150, 16, v189
	v_and_b32_e32 v151, 0xffff0000, v189
	s_mov_b64 s[20:21], 0x1e400c00
	v_pk_add_f32 v[150:151], v[76:77], v[150:151]
	v_pk_add_f32 v[76:77], v[74:75], v[148:149]
	v_lshl_add_u64 v[134:135], v[134:135], 0, s[20:21]
	v_cvt_pk_bf16_f32 v74, v80, v81
	v_cvt_pk_bf16_f32 v75, v84, v85
	v_cvt_pk_bf16_f32 v76, v76, v77
	v_cvt_pk_bf16_f32 v77, v150, v151
	v_lshlrev_b32_e32 v144, 16, v146
	v_and_b32_e32 v145, 0xffff0000, v146
	v_lshlrev_b32_e32 v146, 16, v147
	v_and_b32_e32 v147, 0xffff0000, v147
	global_store_dwordx4 v[134:135], v[74:77], off sc1
	v_lshlrev_b32_e32 v80, 16, v74
	v_and_b32_e32 v81, 0xffff0000, v74
	v_lshlrev_b32_e32 v84, 16, v75
	v_and_b32_e32 v85, 0xffff0000, v75
	v_lshlrev_b32_e32 v74, 16, v76
	v_and_b32_e32 v75, 0xffff0000, v76
	v_lshlrev_b32_e32 v76, 16, v77
	v_and_b32_e32 v77, 0xffff0000, v77

.LBB0_1404:
	s_waitcnt vmcnt(4)
	v_lshlrev_b32_e32 v158, 16, v226
	v_and_b32_e32 v159, 0xffff0000, v226
	v_lshlrev_b32_e32 v160, 16, v227
	v_and_b32_e32 v161, 0xffff0000, v227
	v_lshlrev_b32_e32 v150, 16, v228
	v_and_b32_e32 v151, 0xffff0000, v228
	v_lshlrev_b32_e32 v154, 16, v229
	v_and_b32_e32 v155, 0xffff0000, v229
	v_lshlrev_b32_e32 v152, 16, v230
	v_and_b32_e32 v153, 0xffff0000, v230
	v_lshlrev_b32_e32 v156, 16, v231
	v_and_b32_e32 v157, 0xffff0000, v231
	v_lshlrev_b32_e32 v96, 16, v232
	v_and_b32_e32 v97, 0xffff0000, v232
	v_lshlrev_b32_e32 v100, 16, v233
	v_and_b32_e32 v101, 0xffff0000, v233
	v_lshlrev_b32_e32 v98, 16, v234
	v_and_b32_e32 v99, 0xffff0000, v234
	v_lshlrev_b32_e32 v148, 16, v235
	v_and_b32_e32 v149, 0xffff0000, v235
	v_lshlrev_b32_e32 v86, 16, v236
	v_and_b32_e32 v87, 0xffff0000, v236
	v_lshlrev_b32_e32 v92, 16, v237
	v_and_b32_e32 v93, 0xffff0000, v237
	v_lshlrev_b32_e32 v88, 16, v238
	v_and_b32_e32 v89, 0xffff0000, v238
	v_lshlrev_b32_e32 v94, 16, v239
	v_and_b32_e32 v95, 0xffff0000, v239
	v_lshlrev_b32_e32 v90, 16, v240
	v_and_b32_e32 v91, 0xffff0000, v240
	v_lshlrev_b32_e32 v82, 16, v241
	s_andn2_b64 vcc, exec, s[38:39]
	v_and_b32_e32 v83, 0xffff0000, v241
	s_cbranch_vccnz .LBB0_1406
	v_lshlrev_b32_e32 v162, 16, v190
	v_and_b32_e32 v163, 0xffff0000, v190
	v_lshlrev_b32_e32 v164, 16, v191
	v_and_b32_e32 v165, 0xffff0000, v191
	v_pk_add_f32 v[164:165], v[160:161], v[164:165]
	v_pk_add_f32 v[158:159], v[158:159], v[162:163]
	v_lshlrev_b32_e32 v160, 16, v192
	v_and_b32_e32 v161, 0xffff0000, v192
	v_lshlrev_b32_e32 v162, 16, v193
	v_and_b32_e32 v163, 0xffff0000, v193
	s_mov_b64 s[38:39], 0x31000000
	v_pk_add_f32 v[154:155], v[154:155], v[162:163]
	v_pk_add_f32 v[150:151], v[150:151], v[160:161]
	v_lshl_add_u64 v[84:85], v[146:147], 0, s[38:39]
	v_cvt_pk_bf16_f32 v160, v158, v159
	v_cvt_pk_bf16_f32 v161, v164, v165
	v_cvt_pk_bf16_f32 v162, v150, v151
	v_cvt_pk_bf16_f32 v163, v154, v155
	global_store_dwordx4 v[84:85], v[160:163], off sc1
	v_lshlrev_b32_e32 v150, 16, v162
	v_and_b32_e32 v151, 0xffff0000, v162
	v_lshlrev_b32_e32 v154, 16, v163
	v_and_b32_e32 v155, 0xffff0000, v163
	v_lshlrev_b32_e32 v84, 16, v194
	v_and_b32_e32 v85, 0xffff0000, v194
	v_lshlrev_b32_e32 v162, 16, v195
	v_and_b32_e32 v163, 0xffff0000, v195
	v_pk_add_f32 v[156:157], v[156:157], v[162:163]
	v_pk_add_f32 v[84:85], v[152:153], v[84:85]
	v_lshlrev_b32_e32 v152, 16, v196
	v_and_b32_e32 v153, 0xffff0000, v196
	v_lshlrev_b32_e32 v162, 16, v197
	v_and_b32_e32 v163, 0xffff0000, v197
	s_mov_b64 s[38:39], 0x31000400
	v_pk_add_f32 v[100:101], v[100:101], v[162:163]
	v_pk_add_f32 v[96:97], v[96:97], v[152:153]
	v_lshl_add_u64 v[170:171], v[146:147], 0, s[38:39]
	v_cvt_pk_bf16_f32 v162, v84, v85
	v_cvt_pk_bf16_f32 v163, v156, v157
	v_cvt_pk_bf16_f32 v164, v96, v97
	v_cvt_pk_bf16_f32 v165, v100, v101
	global_store_dwordx4 v[170:171], v[162:165], off sc1
	v_lshlrev_b32_e32 v152, 16, v162
	v_and_b32_e32 v153, 0xffff0000, v162
	v_lshlrev_b32_e32 v156, 16, v163
	v_and_b32_e32 v157, 0xffff0000, v163
	v_lshlrev_b32_e32 v84, 16, v198
	v_and_b32_e32 v85, 0xffff0000, v198
	v_lshlrev_b32_e32 v162, 16, v199
	v_and_b32_e32 v163, 0xffff0000, v199
	v_pk_add_f32 v[148:149], v[148:149], v[162:163]
	v_pk_add_f32 v[84:85], v[98:99], v[84:85]
	v_lshlrev_b32_e32 v98, 16, v200
	v_and_b32_e32 v99, 0xffff0000, v200
	v_lshlrev_b32_e32 v162, 16, v201
	v_and_b32_e32 v163, 0xffff0000, v201
	s_mov_b64 s[38:39], 0x31000800
	v_pk_add_f32 v[92:93], v[92:93], v[162:163]
	v_pk_add_f32 v[86:87], v[86:87], v[98:99]
	v_lshl_add_u64 v[172:173], v[146:147], 0, s[38:39]
	v_lshlrev_b32_e32 v96, 16, v164
	v_and_b32_e32 v97, 0xffff0000, v164
	v_lshlrev_b32_e32 v100, 16, v165
	v_and_b32_e32 v101, 0xffff0000, v165
	v_cvt_pk_bf16_f32 v162, v84, v85
	v_cvt_pk_bf16_f32 v163, v148, v149
	v_cvt_pk_bf16_f32 v164, v86, v87
	v_cvt_pk_bf16_f32 v165, v92, v93
	global_store_dwordx4 v[172:173], v[162:165], off sc1
	v_lshlrev_b32_e32 v98, 16, v162
	v_and_b32_e32 v99, 0xffff0000, v162
	v_lshlrev_b32_e32 v148, 16, v163
	v_and_b32_e32 v149, 0xffff0000, v163
	v_lshlrev_b32_e32 v84, 16, v202
	v_and_b32_e32 v85, 0xffff0000, v202
	v_lshlrev_b32_e32 v162, 16, v203
	v_and_b32_e32 v163, 0xffff0000, v203
	v_pk_add_f32 v[94:95], v[94:95], v[162:163]
	v_pk_add_f32 v[84:85], v[88:89], v[84:85]
	v_lshlrev_b32_e32 v88, 16, v204
	v_and_b32_e32 v89, 0xffff0000, v204
	v_lshlrev_b32_e32 v162, 16, v205
	v_and_b32_e32 v163, 0xffff0000, v205
	s_mov_b64 s[38:39], 0x31000c00
	v_pk_add_f32 v[162:163], v[82:83], v[162:163]
	v_pk_add_f32 v[88:89], v[90:91], v[88:89]
	v_lshl_add_u64 v[146:147], v[146:147], 0, s[38:39]
	v_cvt_pk_bf16_f32 v82, v84, v85
	v_cvt_pk_bf16_f32 v83, v94, v95
	v_cvt_pk_bf16_f32 v84, v88, v89
	v_cvt_pk_bf16_f32 v85, v162, v163
	v_lshlrev_b32_e32 v158, 16, v160
	v_and_b32_e32 v159, 0xffff0000, v160
	v_lshlrev_b32_e32 v160, 16, v161
	v_and_b32_e32 v161, 0xffff0000, v161
	v_lshlrev_b32_e32 v86, 16, v164
	v_and_b32_e32 v87, 0xffff0000, v164
	v_lshlrev_b32_e32 v92, 16, v165
	v_and_b32_e32 v93, 0xffff0000, v165
	global_store_dwordx4 v[146:147], v[82:85], off sc1
	v_lshlrev_b32_e32 v88, 16, v82
	v_and_b32_e32 v89, 0xffff0000, v82
	v_lshlrev_b32_e32 v94, 16, v83
	v_and_b32_e32 v95, 0xffff0000, v83
	v_lshlrev_b32_e32 v90, 16, v84
	v_and_b32_e32 v91, 0xffff0000, v84
	v_lshlrev_b32_e32 v82, 16, v85
	v_and_b32_e32 v83, 0xffff0000, v85
